# P2 NOMAX loop: dead m0 save/restore wrappers around the 4 LDS-DMA loads removed (m0 written directly; 12 fewer SALU per iteration), on top of P1 LDS tables + P2 pointer SALU
# speedup vs baseline: 1.0063x; 1.0001x over previous
; __device__ __forceinline__ void glds16(const void*gsrc,unsigned lds_dst){unsigned keep;
;   asm volatile("s_mov_b32 %0, m0\n\ts_mov_b32 m0, %2\n\ts_nop 0\n\tglobal_load_lds_dwordx4 %1, off\n\ts_mov_b32 m0, %0":"=&s"(keep):"v"(gsrc),"s"(lds_dst):"memory");}
.LBB0_1097:
	s_mov_b32 s7, s89
	s_add_u32 s98, s100, s24
	s_mov_b32 s88, s38
	s_addc_u32 s99, s101, s25
	s_mov_b32 s37, s87
	v_add_u32_e32 v198, s36, v233
	ds_read_b64_tr_b16 v[200:201], v198 offset:24576
	ds_read_b64_tr_b16 v[202:203], v198 offset:25088
	v_add_f32_e32 v98, v82, v83
	v_add_f32_e32 v98, v84, v98
	v_add_f32_e32 v98, v85, v98
	v_add_f32_e32 v98, v86, v98
	v_add_f32_e32 v98, v87, v98
	v_cvt_pk_bf16_f32 v158, v82, v83
	v_cvt_pk_bf16_f32 v159, v84, v85
	s_waitcnt lgkmcnt(9)
	v_mfma_f32_32x32x16_bf16 v[114:129], v[190:193], v[130:133], v[50:65]
	ds_read_b64_tr_b16 v[82:83], v198 offset:28672
	ds_read_b64_tr_b16 v[84:85], v198 offset:29184
	v_add_f32_e32 v98, v88, v98
	v_add_f32_e32 v98, v89, v98
	v_add_f32_e32 v98, v90, v98
	v_add_f32_e32 v146, v91, v98
	s_waitcnt lgkmcnt(10)
	v_mfma_f32_32x32x16_bf16 v[98:113], v[186:189], v[130:133], v[50:65]
	v_cvt_pk_bf16_f32 v160, v86, v87
	v_cvt_pk_bf16_f32 v161, v88, v89
	ds_read_b64_tr_b16 v[86:87], v198 offset:25600
	ds_read_b64_tr_b16 v[88:89], v198 offset:26112
	v_add_f32_e32 v146, v92, v146
	v_add_f32_e32 v146, v93, v146
	v_add_f32_e32 v146, v94, v146
	v_add_f32_e32 v146, v95, v146
	v_cvt_pk_bf16_f32 v154, v90, v91
	v_cvt_pk_bf16_f32 v155, v92, v93
	s_waitcnt lgkmcnt(11)
	v_mfma_f32_32x32x16_bf16 v[114:129], v[182:185], v[134:137], v[114:129]
	ds_read_b64_tr_b16 v[90:91], v198 offset:29696
	ds_read_b64_tr_b16 v[92:93], v198 offset:30208
	s_waitcnt lgkmcnt(12)
	v_mfma_f32_32x32x16_bf16 v[98:113], v[178:181], v[134:137], v[98:113]
	v_add_f32_e32 v146, v96, v146
	v_add_f32_e32 v146, v97, v146
	v_add_f32_e32 v146, v66, v146
	v_add_f32_e32 v146, v67, v146
	v_cvt_pk_bf16_f32 v156, v94, v95
	v_cvt_pk_bf16_f32 v157, v96, v97
	ds_read_b64_tr_b16 v[94:95], v198 offset:26624
	ds_read_b64_tr_b16 v[96:97], v198 offset:27136
	v_add_f32_e32 v146, v68, v146
	v_add_f32_e32 v146, v69, v146
	v_add_f32_e32 v146, v70, v146
	v_add_f32_e32 v146, v71, v146
	v_cvt_pk_bf16_f32 v150, v66, v67
	v_cvt_pk_bf16_f32 v151, v68, v69
	s_waitcnt lgkmcnt(13)
	v_mfma_f32_32x32x16_bf16 v[114:129], v[174:177], v[138:141], v[114:129]
	ds_read_b64_tr_b16 v[66:67], v198 offset:30720
	ds_read_b64_tr_b16 v[68:69], v198 offset:31232
	s_waitcnt lgkmcnt(14)
	v_mfma_f32_32x32x16_bf16 v[98:113], v[170:173], v[138:141], v[98:113]
	v_add_f32_e32 v146, v72, v146
	v_add_f32_e32 v146, v73, v146
	v_add_f32_e32 v146, v74, v146
	v_add_f32_e32 v146, v75, v146
	v_cvt_pk_bf16_f32 v152, v70, v71
	v_cvt_pk_bf16_f32 v153, v72, v73
	ds_read_b64_tr_b16 v[70:71], v198 offset:27648
	ds_read_b64_tr_b16 v[72:73], v198 offset:28160
	v_add_f32_e32 v146, v76, v146
	v_add_f32_e32 v146, v77, v146
	v_add_f32_e32 v146, v78, v146
	v_add_f32_e32 v170, v79, v146
	v_cvt_pk_bf16_f32 v146, v74, v75
	v_cvt_pk_bf16_f32 v147, v76, v77
	s_waitcnt lgkmcnt(14)
	v_mfma_f32_32x32x16_bf16 v[114:129], v[166:169], v[142:145], v[114:129]
	ds_read_b64_tr_b16 v[74:75], v198 offset:31744
	ds_read_b64_tr_b16 v[76:77], v198 offset:32256
	v_mfma_f32_32x32x16_bf16 v[98:113], v[162:165], v[142:145], v[98:113]
	v_add_f32_e32 v148, v80, v170
	v_add_f32_e32 v148, v81, v148
	v_add_f32_e32 v198, 0, v148
	v_cvt_pk_bf16_f32 v148, v78, v79
	v_cvt_pk_bf16_f32 v149, v80, v81
	s_add_i32 m0, s87, s84
	s_nop 0
	global_load_lds_dwordx4 v196, s[98:99]
	s_add_i32 m0, s89, s8
	s_nop 0
	global_load_lds_dwordx4 v194, s[98:99]
	s_waitcnt lgkmcnt(14)
	v_mfma_f32_32x32x16_bf16 v[18:33], v[158:161], v[200:203], v[18:33]
	v_exp_f32_e32 v114, v114
	v_exp_f32_e32 v115, v115
	v_exp_f32_e32 v116, v116
	v_exp_f32_e32 v117, v117
	s_waitcnt lgkmcnt(12)
	v_mfma_f32_32x32x16_bf16 v[34:49], v[158:161], v[82:85], v[34:49]
	v_exp_f32_e32 v118, v118
	v_exp_f32_e32 v119, v119
	v_exp_f32_e32 v120, v120
	v_exp_f32_e32 v121, v121
	v_add_u32_e32 v82, s7, v232
	ds_read_b128 v[78:81], v82
	ds_read_b128 v[162:165], v82 offset:512
	s_waitcnt lgkmcnt(12)
	v_mfma_f32_32x32x16_bf16 v[18:33], v[154:157], v[86:89], v[18:33]
	v_exp_f32_e32 v122, v122
	v_exp_f32_e32 v123, v123
	v_exp_f32_e32 v124, v124
	v_exp_f32_e32 v125, v125
	ds_read_b128 v[166:169], v82 offset:2048
	ds_read_b128 v[170:173], v82 offset:2560
	s_waitcnt lgkmcnt(12)
	v_mfma_f32_32x32x16_bf16 v[34:49], v[154:157], v[90:93], v[34:49]
	v_exp_f32_e32 v126, v126
	v_exp_f32_e32 v127, v127
	v_exp_f32_e32 v128, v128
	v_exp_f32_e32 v129, v129
	ds_read_b128 v[174:177], v82 offset:4096
	ds_read_b128 v[178:181], v82 offset:4608
	s_waitcnt lgkmcnt(12)
	v_mfma_f32_32x32x16_bf16 v[18:33], v[150:153], v[94:97], v[18:33]
	v_exp_f32_e32 v98, v98
	v_exp_f32_e32 v99, v99
	v_exp_f32_e32 v100, v100
	v_exp_f32_e32 v101, v101
	ds_read_b128 v[182:185], v82 offset:6144
	ds_read_b128 v[186:189], v82 offset:6656
	s_waitcnt lgkmcnt(12)
	v_mfma_f32_32x32x16_bf16 v[34:49], v[150:153], v[66:69], v[34:49]
	v_exp_f32_e32 v102, v102
	v_exp_f32_e32 v103, v103
	v_exp_f32_e32 v104, v104
	v_exp_f32_e32 v105, v105
	s_waitcnt lgkmcnt(10)
	v_mfma_f32_32x32x16_bf16 v[18:33], v[146:149], v[70:73], v[18:33]
	v_exp_f32_e32 v106, v106
	v_exp_f32_e32 v107, v107
	v_exp_f32_e32 v108, v108
	v_exp_f32_e32 v109, v109
	s_waitcnt lgkmcnt(8)
	v_mfma_f32_32x32x16_bf16 v[34:49], v[146:149], v[74:77], v[34:49]
	v_exp_f32_e32 v110, v110
	v_exp_f32_e32 v111, v111
	v_exp_f32_e32 v112, v112
	v_exp_f32_e32 v113, v113
	s_waitcnt vmcnt(2) lgkmcnt(0)
	s_barrier
; #define WAIT_BAR(N) asm volatile("s_waitcnt vmcnt(" #N ") lgkmcnt(0)\n\ts_barrier":::"memory")
;   #define RESC() do{ if(resc){ asm volatile("s_waitcnt lgkmcnt(0)":::"memory"); \
;       _Pragma("unroll") for(int d_=0;d_<2;++d_) _Pragma("unroll") for(int r=0;r<16;++r)o[d_][r]*=wsf[crow(r,hi)]; } }while(0)
;   #define ROT() do{sl_prev=sl_cur;sl_cur=sl_next;sl_next=(sl_next==(NSLOT-1)*SLOTB)?0:sl_next+SLOTB;}while(0)
; template<int THRL,bool NOMAX> __device__ __forceinline__ void attn_unit(long rowbase,int NT,int h,int qb,const bf16*Q,const bf16*__restrict__ Kh,const bf16*__restrict__ Vh,bf16*O,char*shm,
;     bool first,bool has_next,long n_rowbase,int n_h,int n_qb,const bf16*__restrict__ n_Kh,bf16x8 (&qr)[4]){
;     ...
;   for(;t+5<NT;t+=2){
;     STEP(pB0,pB1,pA0,pA1,t,true,true,true);     WAIT_BAR(2); RESC(); ROT();
;     STEP(pA0,pA1,pB0,pB1,t+1,true,true,true);   WAIT_BAR(2); RESC(); ROT();
;   }
	s_add_i32 s0, s89, 0x2000
	s_cmpk_lg_i32 s89, 0x4000
	s_cselect_b32 s87, s0, 0
	v_add_u32_e32 v199, s37, v233
	ds_read_b64_tr_b16 v[190:191], v199 offset:24576
	ds_read_b64_tr_b16 v[192:193], v199 offset:25088
	s_waitcnt lgkmcnt(9)
	v_mfma_f32_32x32x16_bf16 v[82:97], v[78:81], v[130:133], v[50:65]
	v_add_f32_e32 v66, v114, v115
	v_add_f32_e32 v66, v116, v66
	v_add_f32_e32 v66, v117, v66
	v_add_f32_e32 v66, v118, v66
	v_add_f32_e32 v66, v119, v66
	v_cvt_pk_bf16_f32 v158, v114, v115
	v_cvt_pk_bf16_f32 v159, v116, v117
	ds_read_b64_tr_b16 v[114:115], v199 offset:28672
	ds_read_b64_tr_b16 v[116:117], v199 offset:29184
	v_add_f32_e32 v66, v120, v66
	v_add_f32_e32 v66, v121, v66
	v_add_f32_e32 v66, v122, v66
	v_add_f32_e32 v146, v123, v66
	s_waitcnt lgkmcnt(10)
	v_mfma_f32_32x32x16_bf16 v[66:81], v[162:165], v[130:133], v[50:65]
	v_cvt_pk_bf16_f32 v160, v118, v119
	v_cvt_pk_bf16_f32 v161, v120, v121
	ds_read_b64_tr_b16 v[118:119], v199 offset:25600
	ds_read_b64_tr_b16 v[120:121], v199 offset:26112
	s_waitcnt lgkmcnt(11)
	v_mfma_f32_32x32x16_bf16 v[82:97], v[166:169], v[134:137], v[82:97]
	v_add_f32_e32 v146, v124, v146
	v_add_f32_e32 v146, v125, v146
	v_add_f32_e32 v146, v126, v146
	v_add_f32_e32 v146, v127, v146
	v_cvt_pk_bf16_f32 v154, v122, v123
	v_cvt_pk_bf16_f32 v155, v124, v125
	ds_read_b64_tr_b16 v[122:123], v199 offset:29696
	ds_read_b64_tr_b16 v[124:125], v199 offset:30208
	s_waitcnt lgkmcnt(12)
	v_mfma_f32_32x32x16_bf16 v[66:81], v[170:173], v[134:137], v[66:81]
	v_add_f32_e32 v146, v128, v146
	v_add_f32_e32 v146, v129, v146
	v_add_f32_e32 v146, v98, v146
	v_add_f32_e32 v146, v99, v146
	v_cvt_pk_bf16_f32 v156, v126, v127
	v_cvt_pk_bf16_f32 v157, v128, v129
	ds_read_b64_tr_b16 v[126:127], v199 offset:26624
	ds_read_b64_tr_b16 v[128:129], v199 offset:27136
	s_waitcnt lgkmcnt(13)
	v_mfma_f32_32x32x16_bf16 v[82:97], v[174:177], v[138:141], v[82:97]
	v_add_f32_e32 v146, v100, v146
	v_add_f32_e32 v146, v101, v146
	v_add_f32_e32 v146, v102, v146
	v_add_f32_e32 v146, v103, v146
	v_cvt_pk_bf16_f32 v150, v98, v99
	v_cvt_pk_bf16_f32 v151, v100, v101
	ds_read_b64_tr_b16 v[98:99], v199 offset:30720
	ds_read_b64_tr_b16 v[100:101], v199 offset:31232
	s_waitcnt lgkmcnt(14)
	v_mfma_f32_32x32x16_bf16 v[66:81], v[178:181], v[138:141], v[66:81]
	v_add_f32_e32 v146, v104, v146
	v_add_f32_e32 v146, v105, v146
	v_add_f32_e32 v146, v106, v146
	v_add_f32_e32 v146, v107, v146
	v_cvt_pk_bf16_f32 v152, v102, v103
	v_cvt_pk_bf16_f32 v153, v104, v105
	ds_read_b64_tr_b16 v[102:103], v199 offset:27648
	ds_read_b64_tr_b16 v[104:105], v199 offset:28160
	s_waitcnt lgkmcnt(14)
	v_mfma_f32_32x32x16_bf16 v[82:97], v[182:185], v[142:145], v[82:97]
	v_add_f32_e32 v146, v108, v146
	v_add_f32_e32 v146, v109, v146
	v_add_f32_e32 v146, v110, v146
	v_add_f32_e32 v162, v111, v146
	v_cvt_pk_bf16_f32 v146, v106, v107
	v_cvt_pk_bf16_f32 v147, v108, v109
	ds_read_b64_tr_b16 v[106:107], v199 offset:31744
	ds_read_b64_tr_b16 v[108:109], v199 offset:32256
	v_mfma_f32_32x32x16_bf16 v[66:81], v[186:189], v[142:145], v[66:81]
	v_add_f32_e32 v148, v112, v162
	v_add_f32_e32 v148, v113, v148
	v_add_f32_e32 v199, 0, v148
	v_cvt_pk_bf16_f32 v148, v110, v111
	v_cvt_pk_bf16_f32 v149, v112, v113
	s_add_i32 m0, s89, s84
	s_nop 0
	global_load_lds_dwordx4 v196, s[100:101]
	s_add_i32 m0, s87, s8
	s_nop 0
	global_load_lds_dwordx4 v194, s[100:101]
	s_waitcnt lgkmcnt(14)
	v_mfma_f32_32x32x16_bf16 v[18:33], v[158:161], v[190:193], v[18:33]
	v_exp_f32_e32 v82, v82
	v_exp_f32_e32 v83, v83
	v_exp_f32_e32 v84, v84
	v_exp_f32_e32 v85, v85
	s_waitcnt lgkmcnt(12)
	v_mfma_f32_32x32x16_bf16 v[34:49], v[158:161], v[114:117], v[34:49]
	v_exp_f32_e32 v86, v86
	v_exp_f32_e32 v87, v87
	v_exp_f32_e32 v88, v88
	v_exp_f32_e32 v89, v89
	v_add_u32_e32 v110, s87, v232
	ds_read_b128 v[190:193], v110
	ds_read_b128 v[186:189], v110 offset:512
	s_waitcnt lgkmcnt(12)
	v_mfma_f32_32x32x16_bf16 v[18:33], v[154:157], v[118:121], v[18:33]
	v_exp_f32_e32 v90, v90
	v_exp_f32_e32 v91, v91
	v_exp_f32_e32 v92, v92
	v_exp_f32_e32 v93, v93
	ds_read_b128 v[182:185], v110 offset:2048
	ds_read_b128 v[178:181], v110 offset:2560
	s_waitcnt lgkmcnt(12)
	v_mfma_f32_32x32x16_bf16 v[34:49], v[154:157], v[122:125], v[34:49]
	v_exp_f32_e32 v94, v94
	v_exp_f32_e32 v95, v95
	v_exp_f32_e32 v96, v96
	v_exp_f32_e32 v97, v97
	ds_read_b128 v[174:177], v110 offset:4096
	ds_read_b128 v[170:173], v110 offset:4608
	s_waitcnt lgkmcnt(12)
	v_mfma_f32_32x32x16_bf16 v[18:33], v[150:153], v[126:129], v[18:33]
	v_exp_f32_e32 v66, v66
	v_exp_f32_e32 v67, v67
	v_exp_f32_e32 v68, v68
	v_exp_f32_e32 v69, v69
	ds_read_b128 v[166:169], v110 offset:6144
	ds_read_b128 v[162:165], v110 offset:6656
	s_waitcnt lgkmcnt(12)
	v_mfma_f32_32x32x16_bf16 v[34:49], v[150:153], v[98:101], v[34:49]
	v_exp_f32_e32 v70, v70
	v_exp_f32_e32 v71, v71
	v_exp_f32_e32 v72, v72
	v_exp_f32_e32 v73, v73
	s_waitcnt lgkmcnt(10)
	v_mfma_f32_32x32x16_bf16 v[18:33], v[146:149], v[102:105], v[18:33]
	v_exp_f32_e32 v74, v74
	v_exp_f32_e32 v75, v75
	v_exp_f32_e32 v76, v76
	v_exp_f32_e32 v77, v77
	s_waitcnt lgkmcnt(8)
	v_mfma_f32_32x32x16_bf16 v[34:49], v[146:149], v[106:109], v[34:49]
	v_exp_f32_e32 v78, v78
	v_exp_f32_e32 v79, v79
	v_exp_f32_e32 v80, v80
	v_exp_f32_e32 v81, v81
	s_add_i32 s0, s87, 0x2000
	s_waitcnt vmcnt(2) lgkmcnt(0)
	s_barrier
	s_cmpk_lg_i32 s87, 0x4000
	v_add_f32_e32 v102, v206, v198
	s_mov_b32 s36, s89
	s_cselect_b32 s89, s0, 0
	s_add_i32 s6, s6, 2
	s_add_i32 s38, s38, 2
	s_add_u32 s100, s100, s14
	s_addc_u32 s101, s101, s15
	s_cmp_ge_u32 s6, s82
	v_add_f32_e32 v206, v102, v199
	s_cbranch_scc0 .LBB0_1097
	s_sub_u32 s98, s100, s62
	s_subb_u32 s99, s101, s63
	s_sub_u32 s98, s98, s14
	s_subb_u32 s99, s99, s15
	v_lshl_add_u64 v[226:227], v[226:227], 0, s[98:99]
	v_lshl_add_u64 v[228:229], v[228:229], 0, s[98:99]
	s_add_i32 s0, s6, -4
	s_cmp_ge_u32 s0, s82
	s_cbranch_scc1 .LBB0_1132
	s_add_i32 s90, s6, -5
